# v76 + duplicate accumulator zeroing removed in 4 GEMM tile loops + rstd stash consumed behind first counted wait + attention V-half: alpha mov dropped, l rescale moved to rare path
# baseline (speedup 1.0000x reference)
; __device__ __forceinline__ void partialSM(f32x16& p0, f32x16& p1, float& m_reg, float& mn, float& alpha) {
;     ...
;   if (__builtin_expect(__all(pmax - m_reg <= THR / SCALE), 1)) { mn = m_reg; alpha = 1.f; }
;   else { mn = fmaxf(m_reg, pmax); alpha = __builtin_amdgcn_exp2f((m_reg - mn) * C); m_reg = mn; }
;   float mnC = -mn * C + 5.f;
;   for (int r = 0; r < 16; ++r) p0[r] = fmaf(p0[r], C, mnC); for (int r = 0; r < 16; ++r) p1[r] = fmaf(p1[r], C, mnC);
;   for (int r = 0; r < 16; ++r) p0[r] = __builtin_amdgcn_exp2f(p0[r]);
; }
; __device__ __forceinline__ void finishSM(f32x16& p0, f32x16& p1, float alpha, float& l_reg, i32x8& pa) {
;   for (int r = 0; r < 16; ++r) p1[r] = __builtin_amdgcn_exp2f(p1[r]);
;   float ps = 0; for (int r = 0; r < 16; ++r) ps += p0[r]; for (int r = 0; r < 16; ++r) ps += p1[r];
;   { auto rr = __builtin_amdgcn_permlane32_swap(__float_as_uint(ps), __float_as_uint(ps), false, false);
;     ps = __uint_as_float(rr[0]) + __uint_as_float(rr[1]); }
;   l_reg = l_reg * alpha + ps;
.Latt_rare:
	v_mov_b32_e32 v229, v228
	s_nop 1
	v_permlane32_swap_b32_e32 v228, v229
	v_max_f32_e32 v228, v228, v229
	v_sub_f32_e32 v229, v228, v227
	v_max_f32_e32 v229, v193, v229
	v_sub_f32_e32 v231, v193, v229
	v_exp_f32_e32 v226, v231
	v_mov_b32_e32 v193, v229
	v_mul_f32_e32 v194, v194, v226
	v_sub_f32_e32 v231, v236, v229
	v_sub_f32_e32 v229, v231, v227
	v_mov_b32_e32 v227, v231
	v_add_f32_e32 v64, v64, v229
	v_add_f32_e32 v65, v65, v229
	v_add_f32_e32 v66, v66, v229
	v_add_f32_e32 v67, v67, v229
	v_add_f32_e32 v68, v68, v229
	v_add_f32_e32 v69, v69, v229
	v_add_f32_e32 v70, v70, v229
	v_add_f32_e32 v71, v71, v229
	v_add_f32_e32 v72, v72, v229
	v_add_f32_e32 v73, v73, v229
	v_add_f32_e32 v74, v74, v229
	v_add_f32_e32 v75, v75, v229
	v_add_f32_e32 v76, v76, v229
	v_add_f32_e32 v77, v77, v229
	v_add_f32_e32 v78, v78, v229
	v_add_f32_e32 v79, v79, v229
	v_add_f32_e32 v80, v80, v229
	v_add_f32_e32 v81, v81, v229
	v_add_f32_e32 v82, v82, v229
	v_add_f32_e32 v83, v83, v229
	v_add_f32_e32 v84, v84, v229
	v_add_f32_e32 v85, v85, v229
	v_add_f32_e32 v86, v86, v229
	v_add_f32_e32 v87, v87, v229
	v_add_f32_e32 v88, v88, v229
	v_add_f32_e32 v89, v89, v229
	v_add_f32_e32 v90, v90, v229
	v_add_f32_e32 v91, v91, v229
	v_add_f32_e32 v92, v92, v229
	v_add_f32_e32 v93, v93, v229
	v_add_f32_e32 v94, v94, v229
	v_add_f32_e32 v95, v95, v229
	v_mov_b32_e32 v160, v227
	v_mov_b32_e32 v161, v227
	v_mov_b32_e32 v162, v227
	v_mov_b32_e32 v163, v227
	v_mov_b32_e32 v164, v227
	v_mov_b32_e32 v165, v227
	v_mov_b32_e32 v166, v227
	v_mov_b32_e32 v167, v227
	v_mov_b32_e32 v168, v227
	v_mov_b32_e32 v169, v227
	v_mov_b32_e32 v170, v227
	v_mov_b32_e32 v171, v227
	v_mov_b32_e32 v172, v227
	v_mov_b32_e32 v173, v227
	v_mov_b32_e32 v174, v227
	v_mov_b32_e32 v175, v227
	s_mov_b32 exec_hi, 0
	ds_write_b32 v222, v226 offset:128
	s_mov_b64 exec, -1
	s_waitcnt lgkmcnt(0)
	ds_read_b128 v[176:179], v223 offset:128
	ds_read_b128 v[180:183], v223 offset:160
	ds_read_b128 v[184:187], v223 offset:192
	ds_read_b128 v[188:191], v223 offset:224
	s_waitcnt lgkmcnt(0)
	v_mul_f32_e32 v0, v0, v176
	v_mul_f32_e32 v1, v1, v177
	v_mul_f32_e32 v2, v2, v178
	v_mul_f32_e32 v3, v3, v179
	v_mul_f32_e32 v4, v4, v180
	v_mul_f32_e32 v5, v5, v181
	v_mul_f32_e32 v6, v6, v182
	v_mul_f32_e32 v7, v7, v183
	v_mul_f32_e32 v8, v8, v184
	v_mul_f32_e32 v9, v9, v185
	v_mul_f32_e32 v10, v10, v186
	v_mul_f32_e32 v11, v11, v187
	v_mul_f32_e32 v12, v12, v188
	v_mul_f32_e32 v13, v13, v189
	v_mul_f32_e32 v14, v14, v190
	v_mul_f32_e32 v15, v15, v191
	v_mul_f32_e32 v16, v16, v176
	v_mul_f32_e32 v17, v17, v177
	v_mul_f32_e32 v18, v18, v178
	v_mul_f32_e32 v19, v19, v179
	v_mul_f32_e32 v20, v20, v180
	v_mul_f32_e32 v21, v21, v181
	v_mul_f32_e32 v22, v22, v182
	v_mul_f32_e32 v23, v23, v183
	v_mul_f32_e32 v24, v24, v184
	v_mul_f32_e32 v25, v25, v185
	v_mul_f32_e32 v26, v26, v186
	v_mul_f32_e32 v27, v27, v187
	v_mul_f32_e32 v28, v28, v188
	v_mul_f32_e32 v29, v29, v189
	v_mul_f32_e32 v30, v30, v190
	v_mul_f32_e32 v31, v31, v191
	v_mul_f32_e32 v32, v32, v176
	v_mul_f32_e32 v33, v33, v177
	v_mul_f32_e32 v34, v34, v178
	v_mul_f32_e32 v35, v35, v179
	v_mul_f32_e32 v36, v36, v180
	v_mul_f32_e32 v37, v37, v181
	v_mul_f32_e32 v38, v38, v182
	v_mul_f32_e32 v39, v39, v183
	v_mul_f32_e32 v40, v40, v184
	v_mul_f32_e32 v41, v41, v185
	v_mul_f32_e32 v42, v42, v186
	v_mul_f32_e32 v43, v43, v187
	v_mul_f32_e32 v44, v44, v188
	v_mul_f32_e32 v45, v45, v189
	v_mul_f32_e32 v46, v46, v190
	v_mul_f32_e32 v47, v47, v191
	v_mul_f32_e32 v48, v48, v176
	v_mul_f32_e32 v49, v49, v177
	v_mul_f32_e32 v50, v50, v178
	v_mul_f32_e32 v51, v51, v179
	v_mul_f32_e32 v52, v52, v180
	v_mul_f32_e32 v53, v53, v181
	v_mul_f32_e32 v54, v54, v182
	v_mul_f32_e32 v55, v55, v183
	v_mul_f32_e32 v56, v56, v184
	v_mul_f32_e32 v57, v57, v185
	v_mul_f32_e32 v58, v58, v186
	v_mul_f32_e32 v59, v59, v187
	v_mul_f32_e32 v60, v60, v188
	v_mul_f32_e32 v61, v61, v189
	v_mul_f32_e32 v62, v62, v190
	v_mul_f32_e32 v63, v63, v191
	s_cmp_eq_u32 s5, 0
	s_cbranch_scc1 .Latt_rare_back_0
	s_cmp_eq_u32 s5, 1
	s_cbranch_scc1 .Latt_rare_back_1
	s_cmp_eq_u32 s5, 2
	s_cbranch_scc1 .Latt_rare_back_2
	s_branch .Latt_rare_back_3
